# LN phases: the 512 sample rows are taken by waves 0 and 1 of every workgroup (256 CUs) instead of all 8 waves of workgroups 0..63
# speedup vs baseline: 1.0067x; 1.0067x over previous
.LBB0_1219:
	s_or_b64 exec, exec, s[0:1]
	s_waitcnt lgkmcnt(0)
	v_mov_b32_e32 v0, v196
	v_readlane_b32 s8, v253, 27
	s_barrier
	v_readlane_b32 s9, v253, 28
	v_readlane_b32 s10, v253, 29
	v_readlane_b32 s11, v253, 30
	v_and_b32_e32 v49, 63, v0
	v_readfirstlane_b32 s3, v0
	v_mov_b32_e32 v0, s10
	v_mov_b32_e32 v1, s11
	v_readlane_b32 s6, v255, 0
	v_readlane_b32 s8, v255, 2
	v_mov_b32_e32 v48, s94
	v_mov_b32_e32 v50, s95
	v_lshlrev_b32_e32 v144, 4, v49
	v_readlane_b32 s7, v255, 1
	v_readlane_b32 s9, v255, 3
	v_readfirstlane_b32 s0, v0
	v_readfirstlane_b32 s1, v1
	s_nop 1
	global_load_dwordx4 v[0:3], v144, s[6:7]
	global_load_dwordx4 v[4:7], v144, s[6:7] offset:1024
	global_load_dwordx4 v[8:11], v144, s[8:9]
	global_load_dwordx4 v[12:15], v144, s[8:9] offset:1024
	global_load_dwordx4 v[16:19], v144, s[6:7] offset:2048
	global_load_dwordx4 v[20:23], v144, s[6:7] offset:3072
	global_load_dwordx4 v[24:27], v144, s[8:9] offset:2048
	global_load_dwordx4 v[28:31], v144, s[8:9] offset:3072
	s_ashr_i32 s3, s3, 6
	v_readlane_b32 s6, v253, 53
	s_add_i32 s10, s6, s3
	s_ashr_i32 s11, s10, 31
	s_lshr_b32 s18, s88, 2
	s_add_i32 s18, s18, s3
	s_cmp_lt_u32 s3, 2
	s_cselect_b32 s18, s18, 0x200
	s_lshl_b64 s[6:7], s[10:11], 12
	s_add_u32 s6, s0, s6
	s_addc_u32 s7, s1, s7
	v_lshl_add_u64 v[32:33], s[6:7], 0, v[144:145]
	s_mov_b32 s3, 0x100000
	global_load_dwordx4 v[108:111], v144, s[6:7]
	global_load_dwordx4 v[104:107], v144, s[6:7] offset:1024
	global_load_dwordx4 v[100:103], v144, s[6:7] offset:2048
	global_load_dwordx4 v[88:91], v144, s[6:7] offset:3072
	s_mov_b64 s[6:7], 0x100000
	v_add_co_u32_e32 v36, vcc, s3, v32
	v_lshl_add_u64 v[44:45], v[32:33], 0, s[6:7]
	s_nop 0
	v_addc_co_u32_e32 v37, vcc, 0, v33, vcc
	global_load_dwordx4 v[32:35], v[44:45], off offset:1024
	global_load_dwordx4 v[40:43], v[44:45], off offset:2048
	s_nop 0
	global_load_dwordx4 v[36:39], v[36:37], off
	s_nop 0
	global_load_dwordx4 v[44:47], v[44:45], off offset:3072
	s_cmpk_lt_i32 s18, 0x200
	v_readfirstlane_b32 s8, v48
	s_cselect_b32 s11, 9, 8
	s_addk_i32 s18, 0x4000
	v_and_b32_e32 v53, 64, v220
	v_readfirstlane_b32 s9, v50
	s_add_u32 s19, s8, 0x306000
	v_xor_b32_e32 v51, 16, v220
	v_add_u32_e32 v53, 64, v53
	s_addc_u32 s20, s9, 0
	v_cmp_lt_i32_e32 vcc, v51, v53
	s_add_u32 s21, s8, 0x10800000
	s_addc_u32 s22, s9, 0
	v_cndmask_b32_e32 v51, v220, v51, vcc
	v_lshlrev_b32_e32 v151, 2, v51
	v_xor_b32_e32 v51, 32, v220
	v_lshlrev_b32_e32 v48, 2, v49
	v_cmp_lt_i32_e32 vcc, v51, v53
	s_add_u32 s23, s8, 0x280000
	v_lshl_add_u64 v[154:155], s[0:1], 0, v[144:145]
	v_lshlrev_b32_e32 v144, 3, v49
	v_or_b32_e32 v50, 0x100, v48
	v_or_b32_e32 v52, 0x200, v48
	v_or_b32_e32 v54, 0x300, v48
	v_cndmask_b32_e32 v51, v220, v51, vcc
	s_addc_u32 s24, s9, 0
	v_lshl_add_u64 v[56:57], s[8:9], 0, v[144:145]
	s_mov_b64 s[8:9], 0x6300000
	s_mov_b32 s3, 0
	v_lshlrev_b32_e32 v158, 2, v51
	v_cmp_eq_u32_e64 s[6:7], 0, v49
	v_lshl_add_u64 v[156:157], v[56:57], 0, s[8:9]
	v_lshlrev_b32_e32 v144, 2, v48
	v_lshlrev_b32_e32 v159, 2, v50
	v_lshlrev_b32_e32 v160, 2, v52
	v_lshlrev_b32_e32 v161, 2, v54
	s_waitcnt vmcnt(0)
	s_branch .LBB0_1221

.LBB0_1434:
	s_or_b64 exec, exec, s[6:7]
	s_mov_b64 s[6:7], -1
	s_and_b64 vcc, exec, s[0:1]
	s_waitcnt lgkmcnt(0)
	s_barrier
	s_cbranch_vccz .LBB0_1467
	v_mov_b32_e32 v0, v196
	v_readlane_b32 s8, v253, 27
	v_readlane_b32 s10, v253, 29
	v_readlane_b32 s11, v253, 30
	v_and_b32_e32 v37, 63, v0
	v_readfirstlane_b32 s6, v0
	v_mov_b32_e32 v0, s10
	v_mov_b32_e32 v1, s11
	v_readlane_b32 s9, v253, 28
	v_readfirstlane_b32 s12, v0
	v_readfirstlane_b32 s13, v1
	v_mov_b32_e32 v0, s94
	v_mov_b32_e32 v1, s95
	v_readlane_b32 s10, v255, 7
	v_readfirstlane_b32 s8, v0
	v_readfirstlane_b32 s9, v1
	s_add_u32 s3, s8, 0x300000
	v_readlane_b32 s14, v255, 11
	s_addc_u32 s20, s9, 0
	v_lshlrev_b32_e32 v144, 4, v37
	v_readlane_b32 s11, v255, 8
	v_readlane_b32 s15, v255, 12
	s_ashr_i32 s6, s6, 6
	v_readlane_b32 s7, v253, 53
	s_nop 1
	global_load_dwordx4 v[0:3], v144, s[10:11]
	global_load_dwordx4 v[4:7], v144, s[10:11] offset:1024
	global_load_dwordx4 v[8:11], v144, s[14:15]
	global_load_dwordx4 v[12:15], v144, s[14:15] offset:1024
	global_load_dwordx4 v[16:19], v144, s[10:11] offset:2048
	global_load_dwordx4 v[20:23], v144, s[10:11] offset:3072
	global_load_dwordx4 v[24:27], v144, s[14:15] offset:2048
	global_load_dwordx4 v[28:31], v144, s[14:15] offset:3072
	s_add_i32 s14, s7, s6
	s_ashr_i32 s15, s14, 31
	s_lshr_b32 s24, s88, 2
	s_add_i32 s24, s24, s6
	s_cmp_lt_u32 s6, 2
	s_cselect_b32 s24, s24, 0x200
	s_lshl_b64 s[6:7], s[14:15], 12
	s_add_u32 s6, s12, s6
	s_addc_u32 s7, s13, s7
	v_lshl_add_u64 v[32:33], s[6:7], 0, v[144:145]
	global_load_dwordx4 v[100:103], v144, s[6:7]
	global_load_dwordx4 v[104:107], v144, s[6:7] offset:1024
	global_load_dwordx4 v[108:111], v144, s[6:7] offset:2048
	global_load_dwordx4 v[96:99], v144, s[6:7] offset:3072
	s_mov_b64 s[6:7], 0x100000
	v_lshl_add_u64 v[34:35], v[32:33], 0, s[6:7]
	s_mov_b32 s6, 0x100000
	v_add_co_u32_e32 v32, vcc, s6, v32
	s_add_u32 s15, s8, 0x6300000
	s_nop 0
	v_addc_co_u32_e32 v33, vcc, 0, v33, vcc
	global_load_dwordx4 v[84:87], v[34:35], off offset:1024
	global_load_dwordx4 v[88:91], v[34:35], off offset:2048
	global_load_dwordx4 v[80:83], v[32:33], off
	global_load_dwordx4 v[92:95], v[34:35], off offset:3072
	v_and_b32_e32 v35, 64, v220
	v_xor_b32_e32 v33, 16, v220
	v_add_u32_e32 v35, 64, v35
	s_addc_u32 s21, s9, 0
	v_cmp_lt_i32_e32 vcc, v33, v35
	s_cmpk_lt_i32 s24, 0x200
	s_cselect_b32 s23, 9, 8
	v_cndmask_b32_e32 v33, v220, v33, vcc
	s_addk_i32 s24, 0x4000
	v_lshlrev_b32_e32 v121, 2, v33
	v_xor_b32_e32 v33, 32, v220
	v_lshlrev_b32_e32 v120, 2, v37
	v_cmp_lt_i32_e32 vcc, v33, v35
	s_add_u32 s25, s8, 0x280000
	v_or_b32_e32 v32, 0x100, v120
	v_or_b32_e32 v34, 0x200, v120
	v_or_b32_e32 v36, 0x300, v120
	v_cndmask_b32_e32 v33, v220, v33, vcc
	s_addc_u32 s26, s9, 0
	v_lshl_add_u64 v[38:39], s[8:9], 0, v[144:145]
	s_mov_b64 s[8:9], 0x10800000
	s_mov_b32 s22, 0
	v_lshlrev_b32_e32 v128, 2, v33
	v_cmp_eq_u32_e64 s[6:7], 0, v37
	v_lshl_add_u64 v[122:123], s[12:13], 0, v[144:145]
	v_lshl_add_u64 v[124:125], v[38:39], 0, s[8:9]
	v_lshlrev_b32_e32 v129, 2, v32
	v_lshlrev_b32_e32 v130, 2, v34
	v_lshlrev_b32_e32 v131, 2, v36
	s_waitcnt vmcnt(0)
	s_branch .LBB0_1437

.LBB0_1467:
	s_and_b64 vcc, exec, s[6:7]
	s_cbranch_vccz .LBB0_1489
	v_mov_b32_e32 v0, v196
	v_readlane_b32 s8, v253, 27
	v_readlane_b32 s9, v253, 28
	v_readlane_b32 s10, v253, 29
	v_readlane_b32 s11, v253, 30
	v_and_b32_e32 v49, 63, v0
	v_readfirstlane_b32 s3, v0
	v_mov_b32_e32 v0, s10
	v_mov_b32_e32 v1, s11
	v_readlane_b32 s6, v255, 5
	v_readlane_b32 s8, v255, 9
	v_mov_b32_e32 v48, s94
	v_mov_b32_e32 v50, s95
	v_lshlrev_b32_e32 v144, 4, v49
	v_readlane_b32 s7, v255, 6
	v_readlane_b32 s9, v255, 10
	v_readfirstlane_b32 s10, v0
	v_readfirstlane_b32 s11, v1
	s_nop 1
	global_load_dwordx4 v[0:3], v144, s[6:7]
	global_load_dwordx4 v[4:7], v144, s[6:7] offset:1024
	global_load_dwordx4 v[8:11], v144, s[8:9]
	global_load_dwordx4 v[12:15], v144, s[8:9] offset:1024
	global_load_dwordx4 v[16:19], v144, s[6:7] offset:2048
	global_load_dwordx4 v[20:23], v144, s[6:7] offset:3072
	global_load_dwordx4 v[24:27], v144, s[8:9] offset:2048
	global_load_dwordx4 v[28:31], v144, s[8:9] offset:3072
	s_ashr_i32 s3, s3, 6
	v_readlane_b32 s6, v253, 53
	s_add_i32 s12, s6, s3
	s_ashr_i32 s13, s12, 31
	s_lshr_b32 s20, s88, 2
	s_add_i32 s20, s20, s3
	s_cmp_lt_u32 s3, 2
	s_cselect_b32 s20, s20, 0x200
	s_lshl_b64 s[6:7], s[12:13], 12
	s_add_u32 s6, s10, s6
	s_addc_u32 s7, s11, s7
	s_waitcnt vmcnt(13)
	v_lshl_add_u64 v[32:33], s[6:7], 0, v[144:145]
	s_mov_b32 s3, 0x100000
	global_load_dwordx4 v[100:103], v144, s[6:7]
	global_load_dwordx4 v[104:107], v144, s[6:7] offset:1024
	global_load_dwordx4 v[108:111], v144, s[6:7] offset:2048
	global_load_dwordx4 v[88:91], v144, s[6:7] offset:3072
	s_mov_b64 s[6:7], 0x100000
	s_waitcnt vmcnt(15)
	v_add_co_u32_e32 v36, vcc, s3, v32
	v_lshl_add_u64 v[44:45], v[32:33], 0, s[6:7]
	s_nop 0
	v_addc_co_u32_e32 v37, vcc, 0, v33, vcc
	global_load_dwordx4 v[32:35], v[44:45], off offset:1024
	global_load_dwordx4 v[40:43], v[44:45], off offset:2048
	s_nop 0
	global_load_dwordx4 v[36:39], v[36:37], off
	s_nop 0
	global_load_dwordx4 v[44:47], v[44:45], off offset:3072
	v_and_b32_e32 v53, 64, v220
	s_cmpk_lt_i32 s20, 0x200
	v_xor_b32_e32 v51, 16, v220
	v_add_u32_e32 v53, 64, v53
	v_readfirstlane_b32 s8, v48
	s_cselect_b32 s13, 9, 8
	s_addk_i32 s20, 0x4000
	v_cmp_lt_i32_e32 vcc, v51, v53
	v_readfirstlane_b32 s9, v50
	s_add_u32 s21, s8, 0x303000
	v_cndmask_b32_e32 v51, v220, v51, vcc
	s_addc_u32 s22, s9, 0
	v_lshlrev_b32_e32 v128, 2, v51
	v_xor_b32_e32 v51, 32, v220
	v_lshlrev_b32_e32 v56, 3, v49
	v_mov_b32_e32 v57, v145
	v_lshlrev_b32_e32 v48, 2, v49
	v_cmp_lt_i32_e32 vcc, v51, v53
	s_add_u32 s23, s8, 0x280000
	v_lshl_add_u64 v[56:57], s[8:9], 0, v[56:57]
	s_mov_b64 s[14:15], 0x6300000
	v_or_b32_e32 v50, 0x100, v48
	v_or_b32_e32 v52, 0x200, v48
	v_or_b32_e32 v54, 0x300, v48
	v_cndmask_b32_e32 v51, v220, v51, vcc
	s_addc_u32 s24, s9, 0
	v_lshl_add_u64 v[122:123], v[56:57], 0, s[14:15]
	v_lshl_add_u64 v[56:57], s[8:9], 0, v[144:145]
	s_mov_b64 s[8:9], 0x10800000
	s_mov_b32 s3, 0
	v_lshlrev_b32_e32 v129, 2, v51
	v_cmp_eq_u32_e64 s[6:7], 0, v49
	v_lshl_add_u64 v[120:121], s[10:11], 0, v[144:145]
	v_lshl_add_u64 v[124:125], v[56:57], 0, s[8:9]
	v_lshlrev_b32_e32 v130, 2, v48
	v_lshlrev_b32_e32 v131, 2, v50
	v_lshlrev_b32_e32 v132, 2, v52
	v_lshlrev_b32_e32 v133, 2, v54
	s_waitcnt vmcnt(0)
	s_branch .LBB0_1470
